# odinstag
# baseline (speedup 1.0000x reference)
.LBB0_242:
	v_readlane_b32 s0, v254, 23
	s_waitcnt vmcnt(0)
	v_mov_b32_e32 v15, v167
	v_mov_b32_e32 v0, s0
	ds_read_b32 v0, v0
	s_movk_i32 s0, 0x45f
	s_waitcnt lgkmcnt(0)
	v_cmp_lt_i32_e32 vcc, s0, v0
	v_readfirstlane_b32 s5, v0
	v_readfirstlane_b32 s26, v15
	s_cbranch_vccnz .LBB0_262
	s_cmp_lt_u32 s5, 96
	s_cbranch_scc1 .Lodin_go
	s_sleep 127
	s_sleep 127
	s_sleep 127
	s_sleep 127
	s_sleep 127
	s_sleep 127
.Lodin_go:
	v_lshlrev_b32_e32 v2, 4, v15
	v_add_u32_e32 v3, 0x2000, v2
	v_ashrrev_i32_e32 v0, 31, v3
	v_lshrrev_b32_e32 v0, 22, v0
	v_add_u32_e32 v0, v3, v0
	v_ashrrev_i32_e32 v0, 10, v0
	v_mul_i32_i24_e32 v5, 0x400, v0
	v_sub_u32_e32 v3, v3, v5
	v_lshrrev_b32_e32 v5, 4, v3
	v_bitop3_b32 v3, v5, v3, 32 bitop3:0x6c
	v_ashrrev_i32_e32 v5, 31, v3
	s_add_u32 s6, s18, 0x12f00000
	v_lshrrev_b32_e32 v5, 26, v5
	s_addc_u32 s9, s19, 0
	v_add_u32_e32 v5, v3, v5
	s_ashr_i32 s17, s5, 31
	v_ashrrev_i32_e32 v10, 6, v5
	v_and_b32_e32 v5, 0xc0, v5
	s_lshr_b32 s0, s17, 29
	v_sub_u32_e32 v3, v3, v5
	s_add_i32 s0, s5, s0
	s_ashr_i32 s38, s26, 6
	v_lshlrev_b32_e32 v4, 5, v0
	v_ashrrev_i16_sdwa v3, v217, sext(v3) dst_sel:DWORD dst_unused:UNUSED_PAD src0_sel:DWORD src1_sel:BYTE_0
	s_ashr_i32 s1, s0, 3
	s_and_b32 s0, s0, -8
	s_ashr_i32 s39, s26, 8
	s_lshl_b32 s14, s38, 10
	v_and_b32_e32 v4, 32, v4
	v_bfe_i32 v11, v3, 0, 16
	s_sub_i32 s0, s5, s0
	v_add_u32_e32 v3, v4, v11
	v_lshlrev_b32_e32 v4, 3, v0
	s_cmp_lt_i32 s0, 0
	s_movk_i32 s22, 0x8d
	v_and_b32_e32 v4, 0xffff0, v4
	s_cselect_b32 s22, s22, 0x8c
	v_add_lshl_u32 v4, v10, v4, 12
	s_mul_i32 s0, s22, s0
	v_lshl_add_u32 v130, v3, 1, v4
	v_bfe_i32 v4, v15, 27, 1
	s_add_i32 s0, s0, s1
	v_lshrrev_b32_e32 v4, 22, v4
	s_mul_hi_i32 s1, s0, 0x92492493
	v_add_u32_e32 v4, v2, v4
	s_add_i32 s1, s1, s0
	v_and_b32_e32 v4, 0xfffffc00, v4
	s_lshr_b32 s22, s1, 31
	s_ashr_i32 s1, s1, 7
	v_sub_u32_e32 v2, v2, v4
	s_add_i32 s1, s1, s22
	v_lshrrev_b32_e32 v4, 4, v2
	s_lshl_b32 s22, s1, 3
	s_mulk_i32 s1, 0xe0
	v_bitop3_b32 v4, v4, v2, 32 bitop3:0x6c
	v_ashrrev_i32_e32 v2, 31, v2
	s_sub_i32 s0, s0, s1
	v_lshrrev_b32_e32 v2, 26, v2
	s_bfe_u32 s1, s0, 0x3001c
	v_ashrrev_i32_e32 v3, 31, v15
	v_add_u32_e32 v2, v4, v2
	s_add_i32 s1, s0, s1
	v_lshrrev_b32_e32 v3, 26, v3
	v_ashrrev_i32_e32 v13, 6, v2
	s_sext_i32_i16 s23, s1
	s_and_b32 s1, s1, 0xfff8
	v_add_u32_e32 v3, v15, v3
	v_mul_i32_i24_e32 v2, 64, v13
	s_sub_i32 s0, s0, s1
	v_ashrrev_i32_e32 v12, 6, v3
	v_sub_u32_e32 v2, v4, v2
	s_sext_i32_i16 s0, s0
	v_lshlrev_b32_e32 v3, 5, v12
	v_ashrrev_i16_sdwa v2, v217, sext(v2) dst_sel:DWORD dst_unused:UNUSED_PAD src0_sel:DWORD src1_sel:BYTE_0
	s_lshr_b32 s24, s23, 3
	s_add_i32 s52, s22, s0
	v_and_b32_e32 v3, 32, v3
	v_bfe_i32 v14, v2, 0, 16
	s_ashr_i32 s53, s52, 31
	s_bfe_i64 s[22:23], s[24:25], 0x100000
	v_add_u32_e32 v2, v3, v14
	v_lshlrev_b32_e32 v3, 3, v12
	s_lshl_b64 s[0:1], s[52:53], 20
	s_lshl_b64 s[22:23], s[22:23], 20
	v_and_b32_e32 v3, 0xffff0, v3
	s_add_u32 s60, s6, s22
	v_add_lshl_u32 v3, v13, v3, 12
	s_addc_u32 s61, s9, s23
	s_add_i32 s22, s14, 0
	v_lshl_add_u32 v132, v2, 1, v3
	s_add_i32 m0, s22, 0x10000
	v_readlane_b32 s23, v254, 61
	global_load_lds_dwordx4 v132, s[60:61]
	s_add_i32 m0, s22, 0x12000
	s_add_u32 s40, s60, 0x80000
	global_load_lds_dwordx4 v130, s[60:61]
	s_addc_u32 s41, s61, 0
	s_add_i32 m0, s22, 0x14000
	v_mov_b32_e32 v133, v1
	global_load_lds_dwordx4 v132, s[40:41]
	s_add_i32 m0, s22, 0x16000
	s_add_u32 s62, s23, s0
	v_readlane_b32 s0, v254, 62
	s_addc_u32 s63, s0, s1
	s_add_i32 s23, s22, 0x2000
	global_load_lds_dwordx4 v130, s[40:41]
	s_mov_b32 m0, s22
	s_add_u32 s0, s62, 0x80000
	global_load_lds_dwordx4 v132, s[62:63]
	s_mov_b32 m0, s23
	s_addc_u32 s1, s63, 0
	s_add_i32 s66, s22, 0x4000
	global_load_lds_dwordx4 v130, s[62:63]
	s_mov_b32 m0, s66
	s_add_i32 s67, s22, 0x6000
	global_load_lds_dwordx4 v132, s[0:1]
	s_mov_b32 m0, s67
	v_mov_b32_e32 v131, v1
	global_load_lds_dwordx4 v130, s[0:1]
	s_cmp_eq_u32 s39, 1
	v_lshl_add_u64 v[8:9], s[60:61], 0, v[132:133]
	v_lshl_add_u64 v[6:7], s[60:61], 0, v[130:131]
	v_lshl_add_u64 v[2:3], s[62:63], 0, v[132:133]
	s_cselect_b64 s[0:1], -1, 0
	s_cmp_lg_u32 s39, 1
	v_lshl_add_u64 v[4:5], s[62:63], 0, v[130:131]
	s_cbranch_scc1 .LBB0_245
	s_barrier
